# adaLN set-up: silu(c) table loop (8 serial load->wait trips) written out, the 16 loads of a thread issued back to back
# speedup vs baseline: 1.0066x; 1.0066x over previous
; #define LAS __attribute__((address_space(3)))
; __device__ __forceinline__ void phase_prep(const Params& P, LAS unsigned char* lds, int l, const XcdBarrier& bar) {
;     ...
;     if (l == 0) {
;     LAS float* sc = (LAS float*)lds;
;     LAS float* red = (LAS float*)(lds + 32768);
;     for (int i = tid; i < NBATCH * DM; i += NTHREADS) { const float v = P.c[i]; sc[i] = v / (1.0f + expf(-v)); }
;     __syncthreads();
.LBB0_261:
	v_ashrrev_i32_e32 v9, 31, v5
	v_mov_b32_e32 v8, v5
	v_ashrrev_i32_e32 v11, 31, v4
	v_mov_b32_e32 v10, v4
	v_lshl_add_u64 v[10:11], v[10:11], 2, s[66:67]
	v_lshl_add_u64 v[8:9], v[8:9], 2, s[66:67]
	global_load_dword v186, v[8:9], off
	global_load_dword v187, v[10:11], off
	v_add_co_u32_e32 v8, vcc, 0x1000, v8
	s_nop 1
	v_addc_co_u32_e32 v9, vcc, 0, v9, vcc
	v_add_co_u32_e32 v10, vcc, 0x1000, v10
	s_nop 1
	v_addc_co_u32_e32 v11, vcc, 0, v11, vcc
	global_load_dword v188, v[8:9], off
	global_load_dword v189, v[10:11], off
	v_add_co_u32_e32 v8, vcc, 0x1000, v8
	s_nop 1
	v_addc_co_u32_e32 v9, vcc, 0, v9, vcc
	v_add_co_u32_e32 v10, vcc, 0x1000, v10
	s_nop 1
	v_addc_co_u32_e32 v11, vcc, 0, v11, vcc
	global_load_dword v190, v[8:9], off
	global_load_dword v191, v[10:11], off
	v_add_co_u32_e32 v8, vcc, 0x1000, v8
	s_nop 1
	v_addc_co_u32_e32 v9, vcc, 0, v9, vcc
	v_add_co_u32_e32 v10, vcc, 0x1000, v10
	s_nop 1
	v_addc_co_u32_e32 v11, vcc, 0, v11, vcc
	global_load_dword v192, v[8:9], off
	global_load_dword v193, v[10:11], off
	v_add_co_u32_e32 v8, vcc, 0x1000, v8
	s_nop 1
	v_addc_co_u32_e32 v9, vcc, 0, v9, vcc
	v_add_co_u32_e32 v10, vcc, 0x1000, v10
	s_nop 1
	v_addc_co_u32_e32 v11, vcc, 0, v11, vcc
	global_load_dword v194, v[8:9], off
	global_load_dword v195, v[10:11], off
	v_add_co_u32_e32 v8, vcc, 0x1000, v8
	s_nop 1
	v_addc_co_u32_e32 v9, vcc, 0, v9, vcc
	v_add_co_u32_e32 v10, vcc, 0x1000, v10
	s_nop 1
	v_addc_co_u32_e32 v11, vcc, 0, v11, vcc
	global_load_dword v196, v[8:9], off
	global_load_dword v197, v[10:11], off
	v_add_co_u32_e32 v8, vcc, 0x1000, v8
	s_nop 1
	v_addc_co_u32_e32 v9, vcc, 0, v9, vcc
	v_add_co_u32_e32 v10, vcc, 0x1000, v10
	s_nop 1
	v_addc_co_u32_e32 v11, vcc, 0, v11, vcc
	global_load_dword v198, v[8:9], off
	global_load_dword v199, v[10:11], off
	v_add_co_u32_e32 v8, vcc, 0x1000, v8
	s_nop 1
	v_addc_co_u32_e32 v9, vcc, 0, v9, vcc
	v_add_co_u32_e32 v10, vcc, 0x1000, v10
	s_nop 1
	v_addc_co_u32_e32 v11, vcc, 0, v11, vcc
	global_load_dword v200, v[8:9], off
	global_load_dword v201, v[10:11], off
	s_waitcnt vmcnt(14)
	v_mov_b32_e32 v7, v186
	v_mov_b32_e32 v10, v187
	v_mul_f32_e32 v8, 0xbfb8aa3b, v7
	v_mul_f32_e32 v9, 0xbfb8aa3b, v10
	v_fma_f32 v11, v7, s4, -v8
	v_rndne_f32_e32 v12, v8
	v_fma_f32 v13, v10, s4, -v9
	v_rndne_f32_e32 v14, v9
	v_fmac_f32_e32 v11, 0xb2a5705f, v7
	v_sub_f32_e32 v8, v8, v12
	v_fmac_f32_e32 v13, 0xb2a5705f, v10
	v_sub_f32_e32 v9, v9, v14
	v_add_f32_e32 v8, v8, v11
	v_add_f32_e32 v9, v9, v13
	v_cvt_i32_f32_e32 v12, v12
	v_cvt_i32_f32_e32 v14, v14
	v_exp_f32_e32 v8, v8
	v_exp_f32_e32 v9, v9
	v_cmp_nlt_f32_e32 vcc, s5, v7
	v_cmp_nlt_f32_e64 s[54:55], s5, v10
	v_ldexp_f32 v8, v8, v12
	v_ldexp_f32 v9, v9, v14
	v_cndmask_b32_e64 v11, 0, v9, s[54:55]
	v_cmp_ngt_f32_e64 s[54:55], s6, v10
	v_cndmask_b32_e32 v8, 0, v8, vcc
	v_cmp_ngt_f32_e32 vcc, s6, v7
	s_nop 1
	v_cndmask_b32_e32 v9, v237, v8, vcc
	v_cndmask_b32_e64 v8, v237, v11, s[54:55]
	v_pk_add_f32 v[8:9], v[8:9], 1.0 op_sel_hi:[1,0]
	s_nop 0
	v_div_scale_f32 v11, s[24:25], v9, v9, v7
	v_div_scale_f32 v13, s[24:25], v8, v8, v10
	v_rcp_f32_e32 v15, v11
	v_rcp_f32_e32 v16, v13
	v_div_scale_f32 v12, vcc, v7, v9, v7
	v_fma_f32 v17, -v11, v15, 1.0
	v_fma_f32 v18, -v13, v16, 1.0
	v_fmac_f32_e32 v15, v17, v15
	v_div_scale_f32 v14, s[54:55], v10, v8, v10
	v_fmac_f32_e32 v16, v18, v16
	v_mul_f32_e32 v17, v12, v15
	v_mul_f32_e32 v18, v14, v16
	v_fma_f32 v19, -v11, v17, v12
	v_fma_f32 v37, -v13, v18, v14
	v_fmac_f32_e32 v17, v19, v15
	v_fmac_f32_e32 v18, v37, v16
	v_fma_f32 v11, -v11, v17, v12
	v_fma_f32 v12, -v13, v18, v14
	v_div_fmas_f32 v11, v11, v15, v17
	s_mov_b64 vcc, s[54:55]
	v_div_fixup_f32 v7, v11, v9, v7
	v_div_fmas_f32 v9, v12, v16, v18
	v_div_fixup_f32 v8, v9, v8, v10
	ds_write2st64_b32 v6, v8, v7 offset1:8
	v_add_u32_e32 v6, 0x1000, v6
	s_waitcnt vmcnt(12)
	v_mov_b32_e32 v7, v188
	v_mov_b32_e32 v10, v189
	v_mul_f32_e32 v8, 0xbfb8aa3b, v7
	v_mul_f32_e32 v9, 0xbfb8aa3b, v10
	v_fma_f32 v11, v7, s4, -v8
	v_rndne_f32_e32 v12, v8
	v_fma_f32 v13, v10, s4, -v9
	v_rndne_f32_e32 v14, v9
	v_fmac_f32_e32 v11, 0xb2a5705f, v7
	v_sub_f32_e32 v8, v8, v12
	v_fmac_f32_e32 v13, 0xb2a5705f, v10
	v_sub_f32_e32 v9, v9, v14
	v_add_f32_e32 v8, v8, v11
	v_add_f32_e32 v9, v9, v13
	v_cvt_i32_f32_e32 v12, v12
	v_cvt_i32_f32_e32 v14, v14
	v_exp_f32_e32 v8, v8
	v_exp_f32_e32 v9, v9
	v_cmp_nlt_f32_e32 vcc, s5, v7
	v_cmp_nlt_f32_e64 s[54:55], s5, v10
	v_ldexp_f32 v8, v8, v12
	v_ldexp_f32 v9, v9, v14
	v_cndmask_b32_e64 v11, 0, v9, s[54:55]
	v_cmp_ngt_f32_e64 s[54:55], s6, v10
	v_cndmask_b32_e32 v8, 0, v8, vcc
	v_cmp_ngt_f32_e32 vcc, s6, v7
	s_nop 1
	v_cndmask_b32_e32 v9, v237, v8, vcc
	v_cndmask_b32_e64 v8, v237, v11, s[54:55]
	v_pk_add_f32 v[8:9], v[8:9], 1.0 op_sel_hi:[1,0]
	s_nop 0
	v_div_scale_f32 v11, s[24:25], v9, v9, v7
	v_div_scale_f32 v13, s[24:25], v8, v8, v10
	v_rcp_f32_e32 v15, v11
	v_rcp_f32_e32 v16, v13
	v_div_scale_f32 v12, vcc, v7, v9, v7
	v_fma_f32 v17, -v11, v15, 1.0
	v_fma_f32 v18, -v13, v16, 1.0
	v_fmac_f32_e32 v15, v17, v15
	v_div_scale_f32 v14, s[54:55], v10, v8, v10
	v_fmac_f32_e32 v16, v18, v16
	v_mul_f32_e32 v17, v12, v15
	v_mul_f32_e32 v18, v14, v16
	v_fma_f32 v19, -v11, v17, v12
	v_fma_f32 v37, -v13, v18, v14
	v_fmac_f32_e32 v17, v19, v15
	v_fmac_f32_e32 v18, v37, v16
	v_fma_f32 v11, -v11, v17, v12
	v_fma_f32 v12, -v13, v18, v14
	v_div_fmas_f32 v11, v11, v15, v17
	s_mov_b64 vcc, s[54:55]
	v_div_fixup_f32 v7, v11, v9, v7
	v_div_fmas_f32 v9, v12, v16, v18
	v_div_fixup_f32 v8, v9, v8, v10
	ds_write2st64_b32 v6, v8, v7 offset1:8
	v_add_u32_e32 v6, 0x1000, v6
	s_waitcnt vmcnt(10)
; __device__ __forceinline__ void phase_prep(const Params& P, LAS unsigned char* lds, int l, const XcdBarrier& bar) {
;     ...
;     for (int i = tid; i < NBATCH * DM; i += NTHREADS) { const float v = P.c[i]; sc[i] = v / (1.0f + expf(-v)); }
	v_mov_b32_e32 v7, v190
	v_mov_b32_e32 v10, v191
	v_mul_f32_e32 v8, 0xbfb8aa3b, v7
	v_mul_f32_e32 v9, 0xbfb8aa3b, v10
	v_fma_f32 v11, v7, s4, -v8
	v_rndne_f32_e32 v12, v8
	v_fma_f32 v13, v10, s4, -v9
	v_rndne_f32_e32 v14, v9
	v_fmac_f32_e32 v11, 0xb2a5705f, v7
	v_sub_f32_e32 v8, v8, v12
	v_fmac_f32_e32 v13, 0xb2a5705f, v10
	v_sub_f32_e32 v9, v9, v14
	v_add_f32_e32 v8, v8, v11
	v_add_f32_e32 v9, v9, v13
	v_cvt_i32_f32_e32 v12, v12
	v_cvt_i32_f32_e32 v14, v14
	v_exp_f32_e32 v8, v8
	v_exp_f32_e32 v9, v9
	v_cmp_nlt_f32_e32 vcc, s5, v7
	v_cmp_nlt_f32_e64 s[54:55], s5, v10
	v_ldexp_f32 v8, v8, v12
	v_ldexp_f32 v9, v9, v14
	v_cndmask_b32_e64 v11, 0, v9, s[54:55]
	v_cmp_ngt_f32_e64 s[54:55], s6, v10
	v_cndmask_b32_e32 v8, 0, v8, vcc
	v_cmp_ngt_f32_e32 vcc, s6, v7
	s_nop 1
	v_cndmask_b32_e32 v9, v237, v8, vcc
	v_cndmask_b32_e64 v8, v237, v11, s[54:55]
	v_pk_add_f32 v[8:9], v[8:9], 1.0 op_sel_hi:[1,0]
	s_nop 0
	v_div_scale_f32 v11, s[24:25], v9, v9, v7
	v_div_scale_f32 v13, s[24:25], v8, v8, v10
	v_rcp_f32_e32 v15, v11
	v_rcp_f32_e32 v16, v13
	v_div_scale_f32 v12, vcc, v7, v9, v7
	v_fma_f32 v17, -v11, v15, 1.0
	v_fma_f32 v18, -v13, v16, 1.0
	v_fmac_f32_e32 v15, v17, v15
	v_div_scale_f32 v14, s[54:55], v10, v8, v10
	v_fmac_f32_e32 v16, v18, v16
	v_mul_f32_e32 v17, v12, v15
	v_mul_f32_e32 v18, v14, v16
	v_fma_f32 v19, -v11, v17, v12
	v_fma_f32 v37, -v13, v18, v14
	v_fmac_f32_e32 v17, v19, v15
	v_fmac_f32_e32 v18, v37, v16
	v_fma_f32 v11, -v11, v17, v12
	v_fma_f32 v12, -v13, v18, v14
	v_div_fmas_f32 v11, v11, v15, v17
	s_mov_b64 vcc, s[54:55]
	v_div_fixup_f32 v7, v11, v9, v7
	v_div_fmas_f32 v9, v12, v16, v18
	v_div_fixup_f32 v8, v9, v8, v10
	ds_write2st64_b32 v6, v8, v7 offset1:8
	v_add_u32_e32 v6, 0x1000, v6
	s_waitcnt vmcnt(8)
	v_mov_b32_e32 v7, v192
	v_mov_b32_e32 v10, v193
	v_mul_f32_e32 v8, 0xbfb8aa3b, v7
	v_mul_f32_e32 v9, 0xbfb8aa3b, v10
	v_fma_f32 v11, v7, s4, -v8
	v_rndne_f32_e32 v12, v8
	v_fma_f32 v13, v10, s4, -v9
	v_rndne_f32_e32 v14, v9
	v_fmac_f32_e32 v11, 0xb2a5705f, v7
	v_sub_f32_e32 v8, v8, v12
	v_fmac_f32_e32 v13, 0xb2a5705f, v10
	v_sub_f32_e32 v9, v9, v14
	v_add_f32_e32 v8, v8, v11
	v_add_f32_e32 v9, v9, v13
	v_cvt_i32_f32_e32 v12, v12
	v_cvt_i32_f32_e32 v14, v14
	v_exp_f32_e32 v8, v8
	v_exp_f32_e32 v9, v9
	v_cmp_nlt_f32_e32 vcc, s5, v7
	v_cmp_nlt_f32_e64 s[54:55], s5, v10
	v_ldexp_f32 v8, v8, v12
	v_ldexp_f32 v9, v9, v14
	v_cndmask_b32_e64 v11, 0, v9, s[54:55]
	v_cmp_ngt_f32_e64 s[54:55], s6, v10
	v_cndmask_b32_e32 v8, 0, v8, vcc
	v_cmp_ngt_f32_e32 vcc, s6, v7
	s_nop 1
	v_cndmask_b32_e32 v9, v237, v8, vcc
	v_cndmask_b32_e64 v8, v237, v11, s[54:55]
	v_pk_add_f32 v[8:9], v[8:9], 1.0 op_sel_hi:[1,0]
	s_nop 0
	v_div_scale_f32 v11, s[24:25], v9, v9, v7
	v_div_scale_f32 v13, s[24:25], v8, v8, v10
	v_rcp_f32_e32 v15, v11
	v_rcp_f32_e32 v16, v13
	v_div_scale_f32 v12, vcc, v7, v9, v7
	v_fma_f32 v17, -v11, v15, 1.0
	v_fma_f32 v18, -v13, v16, 1.0
	v_fmac_f32_e32 v15, v17, v15
	v_div_scale_f32 v14, s[54:55], v10, v8, v10
	v_fmac_f32_e32 v16, v18, v16
	v_mul_f32_e32 v17, v12, v15
	v_mul_f32_e32 v18, v14, v16
	v_fma_f32 v19, -v11, v17, v12
	v_fma_f32 v37, -v13, v18, v14
	v_fmac_f32_e32 v17, v19, v15
	v_fmac_f32_e32 v18, v37, v16
	v_fma_f32 v11, -v11, v17, v12
	v_fma_f32 v12, -v13, v18, v14
	v_div_fmas_f32 v11, v11, v15, v17
	s_mov_b64 vcc, s[54:55]
	v_div_fixup_f32 v7, v11, v9, v7
	v_div_fmas_f32 v9, v12, v16, v18
	v_div_fixup_f32 v8, v9, v8, v10
	ds_write2st64_b32 v6, v8, v7 offset1:8
	v_add_u32_e32 v6, 0x1000, v6
	s_waitcnt vmcnt(6)
	v_mov_b32_e32 v7, v194
	v_mov_b32_e32 v10, v195
	v_mul_f32_e32 v8, 0xbfb8aa3b, v7
	v_mul_f32_e32 v9, 0xbfb8aa3b, v10
	v_fma_f32 v11, v7, s4, -v8
	v_rndne_f32_e32 v12, v8
	v_fma_f32 v13, v10, s4, -v9
	v_rndne_f32_e32 v14, v9
	v_fmac_f32_e32 v11, 0xb2a5705f, v7
	v_sub_f32_e32 v8, v8, v12
	v_fmac_f32_e32 v13, 0xb2a5705f, v10
	v_sub_f32_e32 v9, v9, v14
	v_add_f32_e32 v8, v8, v11
	v_add_f32_e32 v9, v9, v13
	v_cvt_i32_f32_e32 v12, v12
	v_cvt_i32_f32_e32 v14, v14
	v_exp_f32_e32 v8, v8
	v_exp_f32_e32 v9, v9
	v_cmp_nlt_f32_e32 vcc, s5, v7
	v_cmp_nlt_f32_e64 s[54:55], s5, v10
	v_ldexp_f32 v8, v8, v12
	v_ldexp_f32 v9, v9, v14
	v_cndmask_b32_e64 v11, 0, v9, s[54:55]
	v_cmp_ngt_f32_e64 s[54:55], s6, v10
	v_cndmask_b32_e32 v8, 0, v8, vcc
	v_cmp_ngt_f32_e32 vcc, s6, v7
	s_nop 1
	v_cndmask_b32_e32 v9, v237, v8, vcc
	v_cndmask_b32_e64 v8, v237, v11, s[54:55]
	v_pk_add_f32 v[8:9], v[8:9], 1.0 op_sel_hi:[1,0]
	s_nop 0
	v_div_scale_f32 v11, s[24:25], v9, v9, v7
	v_div_scale_f32 v13, s[24:25], v8, v8, v10
	v_rcp_f32_e32 v15, v11
	v_rcp_f32_e32 v16, v13
	v_div_scale_f32 v12, vcc, v7, v9, v7
	v_fma_f32 v17, -v11, v15, 1.0
	v_fma_f32 v18, -v13, v16, 1.0
	v_fmac_f32_e32 v15, v17, v15
	v_div_scale_f32 v14, s[54:55], v10, v8, v10
	v_fmac_f32_e32 v16, v18, v16
	v_mul_f32_e32 v17, v12, v15
	v_mul_f32_e32 v18, v14, v16
	v_fma_f32 v19, -v11, v17, v12
	v_fma_f32 v37, -v13, v18, v14
	v_fmac_f32_e32 v17, v19, v15
	v_fmac_f32_e32 v18, v37, v16
	v_fma_f32 v11, -v11, v17, v12
	v_fma_f32 v12, -v13, v18, v14
	v_div_fmas_f32 v11, v11, v15, v17
	s_mov_b64 vcc, s[54:55]
	v_div_fixup_f32 v7, v11, v9, v7
	v_div_fmas_f32 v9, v12, v16, v18
	v_div_fixup_f32 v8, v9, v8, v10
	ds_write2st64_b32 v6, v8, v7 offset1:8
	v_add_u32_e32 v6, 0x1000, v6
	s_waitcnt vmcnt(4)
; #define LAS __attribute__((address_space(3)))
; __device__ __forceinline__ void phase_prep(const Params& P, LAS unsigned char* lds, int l, const XcdBarrier& bar) {
;     ...
;     if (l == 0) {
;     LAS float* sc = (LAS float*)lds;
;     LAS float* red = (LAS float*)(lds + 32768);
;     for (int i = tid; i < NBATCH * DM; i += NTHREADS) { const float v = P.c[i]; sc[i] = v / (1.0f + expf(-v)); }
;     __syncthreads();
;     float* mod = (float*)(ws + WS_MOD);
;     const int cq = tid & 15, kg = tid >> 4;
; #pragma unroll 1
;     for (int it = wg; it < NLAYER * (NMOD / 64); it += G) {
;         const int ll = it / (NMOD / 64), ch = it % (NMOD / 64), col0 = ch * 64;
;         const float* wp = P.ada_w + ((size_t)ll * DM + kg) * NMOD + col0 + 4 * cq;
	v_mov_b32_e32 v7, v196
	v_mov_b32_e32 v10, v197
	v_mul_f32_e32 v8, 0xbfb8aa3b, v7
	v_mul_f32_e32 v9, 0xbfb8aa3b, v10
	v_fma_f32 v11, v7, s4, -v8
	v_rndne_f32_e32 v12, v8
	v_fma_f32 v13, v10, s4, -v9
	v_rndne_f32_e32 v14, v9
	v_fmac_f32_e32 v11, 0xb2a5705f, v7
	v_sub_f32_e32 v8, v8, v12
	v_fmac_f32_e32 v13, 0xb2a5705f, v10
	v_sub_f32_e32 v9, v9, v14
	v_add_f32_e32 v8, v8, v11
	v_add_f32_e32 v9, v9, v13
	v_cvt_i32_f32_e32 v12, v12
	v_cvt_i32_f32_e32 v14, v14
	v_exp_f32_e32 v8, v8
	v_exp_f32_e32 v9, v9
	v_cmp_nlt_f32_e32 vcc, s5, v7
	v_cmp_nlt_f32_e64 s[54:55], s5, v10
	v_ldexp_f32 v8, v8, v12
	v_ldexp_f32 v9, v9, v14
	v_cndmask_b32_e64 v11, 0, v9, s[54:55]
	v_cmp_ngt_f32_e64 s[54:55], s6, v10
	v_cndmask_b32_e32 v8, 0, v8, vcc
	v_cmp_ngt_f32_e32 vcc, s6, v7
	s_nop 1
	v_cndmask_b32_e32 v9, v237, v8, vcc
	v_cndmask_b32_e64 v8, v237, v11, s[54:55]
	v_pk_add_f32 v[8:9], v[8:9], 1.0 op_sel_hi:[1,0]
	s_nop 0
	v_div_scale_f32 v11, s[24:25], v9, v9, v7
	v_div_scale_f32 v13, s[24:25], v8, v8, v10
	v_rcp_f32_e32 v15, v11
	v_rcp_f32_e32 v16, v13
	v_div_scale_f32 v12, vcc, v7, v9, v7
	v_fma_f32 v17, -v11, v15, 1.0
	v_fma_f32 v18, -v13, v16, 1.0
	v_fmac_f32_e32 v15, v17, v15
	v_div_scale_f32 v14, s[54:55], v10, v8, v10
	v_fmac_f32_e32 v16, v18, v16
	v_mul_f32_e32 v17, v12, v15
	v_mul_f32_e32 v18, v14, v16
	v_fma_f32 v19, -v11, v17, v12
	v_fma_f32 v37, -v13, v18, v14
	v_fmac_f32_e32 v17, v19, v15
	v_fmac_f32_e32 v18, v37, v16
	v_fma_f32 v11, -v11, v17, v12
	v_fma_f32 v12, -v13, v18, v14
	v_div_fmas_f32 v11, v11, v15, v17
	s_mov_b64 vcc, s[54:55]
	v_div_fixup_f32 v7, v11, v9, v7
	v_div_fmas_f32 v9, v12, v16, v18
	v_div_fixup_f32 v8, v9, v8, v10
	ds_write2st64_b32 v6, v8, v7 offset1:8
	v_add_u32_e32 v6, 0x1000, v6
	s_waitcnt vmcnt(2)
	v_mov_b32_e32 v7, v198
	v_mov_b32_e32 v10, v199
	v_mul_f32_e32 v8, 0xbfb8aa3b, v7
	v_mul_f32_e32 v9, 0xbfb8aa3b, v10
	v_fma_f32 v11, v7, s4, -v8
	v_rndne_f32_e32 v12, v8
	v_fma_f32 v13, v10, s4, -v9
	v_rndne_f32_e32 v14, v9
	v_fmac_f32_e32 v11, 0xb2a5705f, v7
	v_sub_f32_e32 v8, v8, v12
	v_fmac_f32_e32 v13, 0xb2a5705f, v10
	v_sub_f32_e32 v9, v9, v14
	v_add_f32_e32 v8, v8, v11
	v_add_f32_e32 v9, v9, v13
	v_cvt_i32_f32_e32 v12, v12
	v_cvt_i32_f32_e32 v14, v14
	v_exp_f32_e32 v8, v8
	v_exp_f32_e32 v9, v9
	v_cmp_nlt_f32_e32 vcc, s5, v7
	v_cmp_nlt_f32_e64 s[54:55], s5, v10
	v_ldexp_f32 v8, v8, v12
	v_ldexp_f32 v9, v9, v14
	v_cndmask_b32_e64 v11, 0, v9, s[54:55]
	v_cmp_ngt_f32_e64 s[54:55], s6, v10
	v_cndmask_b32_e32 v8, 0, v8, vcc
	v_cmp_ngt_f32_e32 vcc, s6, v7
	s_nop 1
	v_cndmask_b32_e32 v9, v237, v8, vcc
	v_cndmask_b32_e64 v8, v237, v11, s[54:55]
	v_pk_add_f32 v[8:9], v[8:9], 1.0 op_sel_hi:[1,0]
	s_nop 0
	v_div_scale_f32 v11, s[24:25], v9, v9, v7
	v_div_scale_f32 v13, s[24:25], v8, v8, v10
	v_rcp_f32_e32 v15, v11
	v_rcp_f32_e32 v16, v13
	v_div_scale_f32 v12, vcc, v7, v9, v7
	v_fma_f32 v17, -v11, v15, 1.0
	v_fma_f32 v18, -v13, v16, 1.0
	v_fmac_f32_e32 v15, v17, v15
	v_div_scale_f32 v14, s[54:55], v10, v8, v10
	v_fmac_f32_e32 v16, v18, v16
	v_mul_f32_e32 v17, v12, v15
	v_mul_f32_e32 v18, v14, v16
	v_fma_f32 v19, -v11, v17, v12
	v_fma_f32 v37, -v13, v18, v14
	v_fmac_f32_e32 v17, v19, v15
	v_fmac_f32_e32 v18, v37, v16
	v_fma_f32 v11, -v11, v17, v12
	v_fma_f32 v12, -v13, v18, v14
	v_div_fmas_f32 v11, v11, v15, v17
	s_mov_b64 vcc, s[54:55]
	v_div_fixup_f32 v7, v11, v9, v7
	v_div_fmas_f32 v9, v12, v16, v18
	v_div_fixup_f32 v8, v9, v8, v10
	ds_write2st64_b32 v6, v8, v7 offset1:8
	v_add_u32_e32 v6, 0x1000, v6
	s_waitcnt vmcnt(0)
	v_mov_b32_e32 v7, v200
	v_mov_b32_e32 v10, v201
	v_mul_f32_e32 v8, 0xbfb8aa3b, v7
	v_mul_f32_e32 v9, 0xbfb8aa3b, v10
	v_fma_f32 v11, v7, s4, -v8
	v_rndne_f32_e32 v12, v8
	v_fma_f32 v13, v10, s4, -v9
	v_rndne_f32_e32 v14, v9
	v_fmac_f32_e32 v11, 0xb2a5705f, v7
	v_sub_f32_e32 v8, v8, v12
	v_fmac_f32_e32 v13, 0xb2a5705f, v10
	v_sub_f32_e32 v9, v9, v14
	v_add_f32_e32 v8, v8, v11
	v_add_f32_e32 v9, v9, v13
	v_cvt_i32_f32_e32 v12, v12
	v_cvt_i32_f32_e32 v14, v14
	v_exp_f32_e32 v8, v8
	v_exp_f32_e32 v9, v9
	v_cmp_nlt_f32_e32 vcc, s5, v7
	v_cmp_nlt_f32_e64 s[54:55], s5, v10
	v_ldexp_f32 v8, v8, v12
	v_ldexp_f32 v9, v9, v14
	v_cndmask_b32_e64 v11, 0, v9, s[54:55]
	v_cmp_ngt_f32_e64 s[54:55], s6, v10
	v_cndmask_b32_e32 v8, 0, v8, vcc
	v_cmp_ngt_f32_e32 vcc, s6, v7
	s_nop 1
	v_cndmask_b32_e32 v9, v237, v8, vcc
	v_cndmask_b32_e64 v8, v237, v11, s[54:55]
	v_pk_add_f32 v[8:9], v[8:9], 1.0 op_sel_hi:[1,0]
	s_nop 0
	v_div_scale_f32 v11, s[24:25], v9, v9, v7
	v_div_scale_f32 v13, s[24:25], v8, v8, v10
	v_rcp_f32_e32 v15, v11
	v_rcp_f32_e32 v16, v13
	v_div_scale_f32 v12, vcc, v7, v9, v7
	v_fma_f32 v17, -v11, v15, 1.0
	v_fma_f32 v18, -v13, v16, 1.0
	v_fmac_f32_e32 v15, v17, v15
	v_div_scale_f32 v14, s[54:55], v10, v8, v10
	v_fmac_f32_e32 v16, v18, v16
	v_mul_f32_e32 v17, v12, v15
	v_mul_f32_e32 v18, v14, v16
	v_fma_f32 v19, -v11, v17, v12
	v_fma_f32 v37, -v13, v18, v14
	v_fmac_f32_e32 v17, v19, v15
	v_fmac_f32_e32 v18, v37, v16
	v_fma_f32 v11, -v11, v17, v12
	v_fma_f32 v12, -v13, v18, v14
	v_div_fmas_f32 v11, v11, v15, v17
	s_mov_b64 vcc, s[54:55]
	v_div_fixup_f32 v7, v11, v9, v7
	v_div_fmas_f32 v9, v12, v16, v18
	v_div_fixup_f32 v8, v9, v8, v10
	ds_write2st64_b32 v6, v8, v7 offset1:8
	v_add_u32_e32 v6, 0x1000, v6
	v_add_u32_e32 v2, -16, v2
	v_add_u32_e32 v5, 0x2000, v5
	v_add_u32_e32 v4, 0x2000, v4
	s_mov_b64 s[60:61], exec
	s_or_b64 exec, exec, s[60:61]
	s_mov_b64 s[54:55], 0
	s_mov_b64 s[60:61], exec
	v_readlane_b32 s24, v247, 43
	v_readlane_b32 s25, v247, 44
	s_and_b64 s[24:25], s[60:61], s[24:25]
	s_mov_b64 exec, s[24:25]
	s_mov_b64 s[54:55], exec
	v_lshlrev_b32_e32 v5, 2, v72
	s_or_b64 exec, exec, s[60:61]
	s_orn2_b64 s[54:55], s[54:55], exec
	v_mov_b32_e32 v4, v72
	v_readlane_b32 s79, v250, 28
	s_movk_i32 s76, 0x5ff
	s_mov_b32 s77, 0x13ff1000
